# grid barrier: non-last workgroups poll the top generation word directly; per-XCD republish atomic dropped
# speedup vs baseline: 1.0103x; 1.0103x over previous
.LBB0_107:
	s_or_b64 exec, exec, s[8:9]
	v_cvt_f32_u32_e32 v4, v2
	s_waitcnt vmcnt(0)
	v_readfirstlane_b32 s2, v3
	v_sub_u32_e32 v3, 0, v2
	v_rcp_iflag_f32_e32 v4, v4
	v_add_u32_e32 v5, s2, v1
	v_mul_f32_e32 v4, 0x4f7ffffe, v4
	v_cvt_u32_f32_e32 v4, v4
	v_mul_lo_u32 v1, v3, v4
	v_mul_hi_u32 v1, v4, v1
	v_add_u32_e32 v1, v4, v1
	v_mul_hi_u32 v1, v5, v1
	v_mul_lo_u32 v3, v1, v2
	v_sub_u32_e32 v3, v5, v3
	v_add_u32_e32 v4, 1, v1
	v_cmp_ge_u32_e32 vcc, v3, v2
	s_nop 1
	v_cndmask_b32_e32 v1, v1, v4, vcc
	v_sub_u32_e32 v4, v3, v2
	v_cndmask_b32_e32 v3, v3, v4, vcc
	v_add_u32_e32 v4, 1, v1
	v_cmp_ge_u32_e32 vcc, v3, v2
	v_add_u32_e32 v3, 1, v5
	s_nop 0
	v_cndmask_b32_e32 v1, v1, v4, vcc
	v_mul_lo_u32 v4, v2, v1
	v_add_u32_e32 v2, v4, v2
	v_cmp_ne_u32_e32 vcc, v3, v2
	s_and_saveexec_b64 s[2:3], vcc
	s_xor_b64 s[6:7], exec, s[2:3]
	s_cbranch_execz .LBB0_121
	s_waitcnt lgkmcnt(0)
	v_mov_b32_e32 v0, 0x3100
	global_load_dword v0, v0, s[36:37] offset:1024 sc1
	s_add_u32 s10, s36, 0x3500
	s_addc_u32 s11, s37, 0
	s_waitcnt vmcnt(0)
	v_cmp_eq_u32_e32 vcc, v0, v1
	s_and_saveexec_b64 s[8:9], vcc
	s_cbranch_execz .LBB0_120
	s_mov_b32 s2, 1
	s_mov_b64 s[12:13], 0
	v_mov_b32_e32 v0, 0
	s_branch .LBB0_111

.LBB0_138:
	s_or_b64 exec, exec, s[6:7]
	s_mov_b64 s[6:7], exec
	v_mbcnt_lo_u32_b32 v0, s6, 0
	v_mbcnt_hi_u32_b32 v0, s7, v0
	v_cmp_eq_u32_e32 vcc, 0, v0
	s_waitcnt vmcnt(0)
	buffer_inv sc1
	s_and_saveexec_b64 s[8:9], vcc
	s_cbranch_execz .LBB0_140
	s_bcnt1_i32_b64 s2, s[6:7]
.LBB0_140:
	s_or_b64 exec, exec, s[8:9]
	s_waitcnt vmcnt(0)

.LBB0_342:
	s_or_b64 exec, exec, s[8:9]
	v_cvt_f32_u32_e32 v4, v2
	s_waitcnt vmcnt(0)
	v_readfirstlane_b32 s2, v3
	v_sub_u32_e32 v3, 0, v2
	v_rcp_iflag_f32_e32 v4, v4
	v_add_u32_e32 v5, s2, v1
	v_mul_f32_e32 v4, 0x4f7ffffe, v4
	v_cvt_u32_f32_e32 v4, v4
	v_mul_lo_u32 v1, v3, v4
	v_mul_hi_u32 v1, v4, v1
	v_add_u32_e32 v1, v4, v1
	v_mul_hi_u32 v1, v5, v1
	v_mul_lo_u32 v3, v1, v2
	v_sub_u32_e32 v3, v5, v3
	v_add_u32_e32 v4, 1, v1
	v_cmp_ge_u32_e32 vcc, v3, v2
	s_nop 1
	v_cndmask_b32_e32 v1, v1, v4, vcc
	v_sub_u32_e32 v4, v3, v2
	v_cndmask_b32_e32 v3, v3, v4, vcc
	v_add_u32_e32 v4, 1, v1
	v_cmp_ge_u32_e32 vcc, v3, v2
	v_add_u32_e32 v3, 1, v5
	s_nop 0
	v_cndmask_b32_e32 v1, v1, v4, vcc
	v_mul_lo_u32 v4, v2, v1
	v_add_u32_e32 v2, v4, v2
	v_cmp_ne_u32_e32 vcc, v3, v2
	s_and_saveexec_b64 s[6:7], vcc
	s_xor_b64 s[6:7], exec, s[6:7]
	s_cbranch_execz .LBB0_356
	s_waitcnt lgkmcnt(0)
	v_mov_b32_e32 v0, 0x3100
	global_load_dword v0, v0, s[36:37] offset:1024 sc1
	s_add_u32 s10, s36, 0x3500
	s_addc_u32 s11, s37, 0
	s_waitcnt vmcnt(0)
	v_cmp_eq_u32_e32 vcc, v0, v1
	s_and_saveexec_b64 s[8:9], vcc
	s_cbranch_execz .LBB0_355
	s_mov_b32 s2, 1
	s_mov_b64 s[12:13], 0
	v_mov_b32_e32 v0, 0
	s_branch .LBB0_346

.LBB0_373:
	s_or_b64 exec, exec, s[6:7]
	s_mov_b64 s[6:7], exec
	v_mbcnt_lo_u32_b32 v0, s6, 0
	v_mbcnt_hi_u32_b32 v0, s7, v0
	v_cmp_eq_u32_e32 vcc, 0, v0
	s_waitcnt vmcnt(0)
	buffer_inv sc1
	s_and_saveexec_b64 s[8:9], vcc
	s_cbranch_execz .LBB0_375
	s_bcnt1_i32_b64 s2, s[6:7]
.LBB0_375:
	s_or_b64 exec, exec, s[8:9]
	s_waitcnt vmcnt(0)

.LBB0_485:
	s_or_b64 exec, exec, s[6:7]
	s_mov_b64 s[6:7], exec
	v_mbcnt_lo_u32_b32 v0, s6, 0
	v_mbcnt_hi_u32_b32 v0, s7, v0
	v_cmp_eq_u32_e32 vcc, 0, v0
	s_waitcnt vmcnt(0)
	buffer_inv sc1
	s_and_saveexec_b64 s[8:9], vcc
	s_cbranch_execz .LBB0_487
	s_bcnt1_i32_b64 s2, s[6:7]
.LBB0_487:
	s_or_b64 exec, exec, s[8:9]
	s_waitcnt vmcnt(0)

.LBB0_563:
	s_or_b64 exec, exec, s[6:7]
	s_mov_b64 s[6:7], exec
	v_mbcnt_lo_u32_b32 v0, s6, 0
	v_mbcnt_hi_u32_b32 v0, s7, v0
	v_cmp_eq_u32_e32 vcc, 0, v0
	s_waitcnt vmcnt(0)
	buffer_inv sc1
	s_and_saveexec_b64 s[8:9], vcc
	s_cbranch_execz .LBB0_565
	s_bcnt1_i32_b64 s2, s[6:7]
.LBB0_565:
	s_or_b64 exec, exec, s[8:9]
	s_waitcnt vmcnt(0)

.LBB0_626:
	s_or_b64 exec, exec, s[6:7]
	s_mov_b64 s[6:7], exec
	v_mbcnt_lo_u32_b32 v0, s6, 0
	v_mbcnt_hi_u32_b32 v0, s7, v0
	v_cmp_eq_u32_e32 vcc, 0, v0
	s_waitcnt vmcnt(0)
	buffer_inv sc1
	s_and_saveexec_b64 s[8:9], vcc
	s_cbranch_execz .LBB0_628
	s_bcnt1_i32_b64 s2, s[6:7]
.LBB0_628:
	s_or_b64 exec, exec, s[8:9]
	s_waitcnt vmcnt(0)

.LBB0_681:
	s_or_b64 exec, exec, s[6:7]
	s_mov_b64 s[6:7], exec
	v_mbcnt_lo_u32_b32 v0, s6, 0
	v_mbcnt_hi_u32_b32 v0, s7, v0
	v_cmp_eq_u32_e32 vcc, 0, v0
	s_waitcnt vmcnt(0)
	buffer_inv sc1
	s_and_saveexec_b64 s[8:9], vcc
	s_cbranch_execz .LBB0_683
	s_bcnt1_i32_b64 s2, s[6:7]
.LBB0_683:
	s_or_b64 exec, exec, s[8:9]
	s_waitcnt vmcnt(0)

.LBB0_744:
	s_or_b64 exec, exec, s[6:7]
	s_mov_b64 s[6:7], exec
	v_mbcnt_lo_u32_b32 v0, s6, 0
	v_mbcnt_hi_u32_b32 v0, s7, v0
	v_cmp_eq_u32_e32 vcc, 0, v0
	s_waitcnt vmcnt(0)
	buffer_inv sc1
	s_and_saveexec_b64 s[8:9], vcc
	s_cbranch_execz .LBB0_746
	s_bcnt1_i32_b64 s2, s[6:7]
.LBB0_746:
	s_or_b64 exec, exec, s[8:9]
	s_waitcnt vmcnt(0)

.LBB0_807:
	s_or_b64 exec, exec, s[6:7]
	s_mov_b64 s[6:7], exec
	v_mbcnt_lo_u32_b32 v0, s6, 0
	v_mbcnt_hi_u32_b32 v0, s7, v0
	v_cmp_eq_u32_e32 vcc, 0, v0
	s_waitcnt vmcnt(0)
	buffer_inv sc1
	s_and_saveexec_b64 s[8:9], vcc
	s_cbranch_execz .LBB0_809
	s_bcnt1_i32_b64 s2, s[6:7]
.LBB0_809:
	s_or_b64 exec, exec, s[8:9]
	s_waitcnt vmcnt(0)

.LBB0_862:
	s_or_b64 exec, exec, s[6:7]
	s_mov_b64 s[6:7], exec
	v_mbcnt_lo_u32_b32 v0, s6, 0
	v_mbcnt_hi_u32_b32 v0, s7, v0
	v_cmp_eq_u32_e32 vcc, 0, v0
	s_waitcnt vmcnt(0)
	buffer_inv sc1
	s_and_saveexec_b64 s[8:9], vcc
	s_cbranch_execz .LBB0_864
	s_bcnt1_i32_b64 s2, s[6:7]
.LBB0_864:
	s_or_b64 exec, exec, s[8:9]
	s_waitcnt vmcnt(0)

.LBB0_1578:
	s_or_b64 exec, exec, s[6:7]
	s_mov_b64 s[6:7], exec
	v_mbcnt_lo_u32_b32 v0, s6, 0
	v_mbcnt_hi_u32_b32 v0, s7, v0
	v_cmp_eq_u32_e32 vcc, 0, v0
	s_waitcnt vmcnt(0)
	buffer_inv sc1
	s_and_saveexec_b64 s[8:9], vcc
	s_cbranch_execz .LBB0_1580
	s_bcnt1_i32_b64 s2, s[6:7]
.LBB0_1580:
	s_or_b64 exec, exec, s[8:9]
	s_waitcnt vmcnt(0)

.LBB0_1677:
	s_or_b64 exec, exec, s[6:7]
	s_mov_b64 s[6:7], exec
	v_mbcnt_lo_u32_b32 v0, s6, 0
	v_mbcnt_hi_u32_b32 v0, s7, v0
	v_cmp_eq_u32_e32 vcc, 0, v0
	s_waitcnt vmcnt(0)
	buffer_inv sc1
	s_and_saveexec_b64 s[8:9], vcc
	s_cbranch_execz .LBB0_1679
	s_bcnt1_i32_b64 s2, s[6:7]
.LBB0_1679:
	s_or_b64 exec, exec, s[8:9]
	s_waitcnt vmcnt(0)

.LBB0_1740:
	s_or_b64 exec, exec, s[6:7]
	s_mov_b64 s[6:7], exec
	v_mbcnt_lo_u32_b32 v0, s6, 0
	v_mbcnt_hi_u32_b32 v0, s7, v0
	v_cmp_eq_u32_e32 vcc, 0, v0
	s_waitcnt vmcnt(0)
	buffer_inv sc1
	s_and_saveexec_b64 s[8:9], vcc
	s_cbranch_execz .LBB0_1742
	s_bcnt1_i32_b64 s2, s[6:7]
.LBB0_1742:
	s_or_b64 exec, exec, s[8:9]
	s_waitcnt vmcnt(0)

.LBB0_1795:
	s_or_b64 exec, exec, s[6:7]
	s_mov_b64 s[6:7], exec
	v_mbcnt_lo_u32_b32 v0, s6, 0
	v_mbcnt_hi_u32_b32 v0, s7, v0
	v_cmp_eq_u32_e32 vcc, 0, v0
	s_waitcnt vmcnt(0)
	buffer_inv sc1
	s_and_saveexec_b64 s[8:9], vcc
	s_cbranch_execz .LBB0_1797
	s_bcnt1_i32_b64 s2, s[6:7]
.LBB0_1797:
	s_or_b64 exec, exec, s[8:9]
	s_waitcnt vmcnt(0)

.LBB0_1858:
	s_or_b64 exec, exec, s[6:7]
	s_mov_b64 s[6:7], exec
	v_mbcnt_lo_u32_b32 v0, s6, 0
	v_mbcnt_hi_u32_b32 v0, s7, v0
	v_cmp_eq_u32_e32 vcc, 0, v0
	s_waitcnt vmcnt(0)
	buffer_inv sc1
	s_and_saveexec_b64 s[8:9], vcc
	s_cbranch_execz .LBB0_1860
	s_bcnt1_i32_b64 s2, s[6:7]
.LBB0_1860:
	s_or_b64 exec, exec, s[8:9]
	s_waitcnt vmcnt(0)

.LBB0_1921:
	s_or_b64 exec, exec, s[6:7]
	s_mov_b64 s[6:7], exec
	v_mbcnt_lo_u32_b32 v0, s6, 0
	v_mbcnt_hi_u32_b32 v0, s7, v0
	v_cmp_eq_u32_e32 vcc, 0, v0
	s_waitcnt vmcnt(0)
	buffer_inv sc1
	s_and_saveexec_b64 s[8:9], vcc
	s_cbranch_execz .LBB0_1923
	s_bcnt1_i32_b64 s2, s[6:7]
.LBB0_1923:
	s_or_b64 exec, exec, s[8:9]
	s_waitcnt vmcnt(0)
